# P4 ticket atomic no longer waits for the previous pair's store drain; P2a S3 first block hazard pad (8 bytes); otherwise as previous best
# speedup vs baseline: 1.0167x; 1.0045x over previous
; #define LAS __attribute__((address_space(3)))
; __device__ __forceinline__ void gdn_prep_phase(LAS unsigned char* lds, const GdnPrepArgs& A, int bid, int G, const unsigned char* zero_page) {
;     ...
;         for (int reg = 0; reg < 16; ++reg) {
;             const int i = 32 * rt + (reg & 3) + 8 * (reg >> 2) + 4 * hh; const float val = acc[reg];
;             const float ef = __expf(sc[i] - gfj), eb = __expf(sc[64 + i] - gbj);
;             if (which == 0) {
;                 const float lf = (i > j) ? sc[128 + i] * val * ef : 0.f, lb = (i < j) ? sc[192 + i] * val * eb : 0.f;
;                 ((LAS float*)(lds + L_LPF))[i * 64 + (j & 3) * 16 + (j >> 2)] = lf;
;                 const int i2 = 63 - i, j2 = 63 - j;
;                 ((LAS float*)(lds + L_LPB))[i2 * 64 + (j2 & 3) * 16 + (j2 >> 2)] = lb;
.LBB0_211:
	s_andn2_b64 vcc, exec, s[46:47]
	s_cbranch_vccnz .LBB0_217
	s_nop 0
	s_nop 0
	ds_read2st64_b32 v[44:45], v72 offset0:2 offset1:3
	v_readlane_b32 s46, v255, 15
	v_readlane_b32 s47, v255, 16
	s_waitcnt lgkmcnt(0)
	v_mul_f32_e32 v44, v2, v44
	v_mul_f32_e32 v45, v2, v45
	v_mul_f32_e32 v44, v35, v44
	v_mul_f32_e32 v45, v34, v45
	v_cndmask_b32_e64 v44, 0, v44, s[46:47]
	v_cndmask_b32_e64 v45, 0, v45, s[6:7]
	ds_write_b32 v192, v44
	ds_write_b32 v73, v45

; #define LAS __attribute__((address_space(3)))
; __global__ void __launch_bounds__(512, 2) mega(MegaArgs a) {
;     ...
;                 for (;;) {
;                     if (tid == 0) ((LAS unsigned*)(lds + LDS_BAR))[3] = __hip_atomic_fetch_add(qhead, 2u, __ATOMIC_RELAXED, __HIP_MEMORY_SCOPE_AGENT);
;                     __syncthreads();
;                     const int j0 = (int)((LAS unsigned*)(lds + LDS_BAR))[3];
;                     __syncthreads();
.LBB0_671:
	s_and_saveexec_b64 s[2:3], s[88:89]
	s_cbranch_execz .LBB0_675
	s_mov_b64 s[38:39], exec
	s_nop 0
	v_mbcnt_lo_u32_b32 v2, s38, 0
	v_mbcnt_hi_u32_b32 v2, s39, v2
	v_cmp_eq_u32_e32 vcc, 0, v2
	s_and_saveexec_b64 s[4:5], vcc
	s_cbranch_execz .LBB0_674
	s_bcnt1_i32_b64 s34, s[38:39]
	s_lshl_b32 s34, s34, 1
	v_mov_b32_e32 v3, s34
	global_atomic_add v3, v131, v3, s[36:37] sc0
